# code placement: hot loop heads (SwiGLU and Resid K-loops, attention body b) re-phased to 0 mod 8 bytes with s_nop pads
# speedup vs baseline: 1.0024x; 1.0024x over previous
; __device__ __forceinline__ u32x4 gload16_asm(const void* p) { u32x4 r; asm volatile("global_load_dwordx4 %0, %1, off" : "=v"(r) : "v"(p) : "memory"); return r; }
; __device__ __forceinline__ void attn_phase(const Args& a, LAS unsigned char* lds, const bf16* Qn, const bf16* Kn, const bf16* Vt, bf16* O, float* stash, int tid, int lane, int wave) {
;     ...
;             for (int tp = 0; tp < NT; tp += 2) {
; #pragma unroll
;               for (int hh = 0; hh < 2; ++hh) {
;                 const int t = tp + hh;
;                 if (t + 2 < NT) { kreg[hh] = gload16_asm(Kp + (size_t)(t + 2) * 4096); vreg0[hh] = gload16_asm(Vp + 64 * (t + 2)); vreg1[hh] = gload16_asm(Vp + (size_t)64 * SEQ + 64 * (t + 2)); }
;                 if (t <= td) {
.LBB0_126:
	s_cmp_ge_i32 s2, s30
	s_cbranch_scc1 .LBB0_122
	s_nop 0

; #define LAS __attribute__((address_space(3)))
; __device__ __forceinline__ unsigned pk2(float lo, float hi) { f32x2 v = {lo, hi}; bf16x2_t b = __builtin_convertvector(v, bf16x2_t); return __builtin_bit_cast(unsigned, b); }
; __device__ __forceinline__ void attn_phase(const Args& a, LAS unsigned char* lds, const bf16* Qn, const bf16* Kn, const bf16* Vt, bf16* O, float* stash, int tid, int lane, int wave) {
;     ...
; #pragma unroll
;                     for (int r = 0; r < 16; ++r) { p0[r] = __builtin_amdgcn_exp2f(p0[r]); p1[r] = __builtin_amdgcn_exp2f(p1[r]); }
;                     {
;                         const f32x16 ps = p0 + p1;
;                         f32x2 s2 = (f32x2){ps[0], ps[1]} + (f32x2){ps[2], ps[3]};
; #pragma unroll
;                         for (int r = 4; r < 16; r += 2) s2 += (f32x2){ps[r], ps[r + 1]};
;                         lsum += s2.x + s2.y;
;                     }
;                     bf16x8 pf[4];
; #pragma unroll
;                     for (int s4 = 0; s4 < 4; ++s4) {
;                         u32x4 w;
;                         if (s4 < 2) { w.x = pk2(p0[8 * s4 + 0], p0[8 * s4 + 1]); w.y = pk2(p0[8 * s4 + 2], p0[8 * s4 + 3]); w.z = pk2(p0[8 * s4 + 4], p0[8 * s4 + 5]); w.w = pk2(p0[8 * s4 + 6], p0[8 * s4 + 7]); }
;                         else { const int q = s4 - 2; w.x = pk2(p1[8 * q + 0], p1[8 * q + 1]); w.y = pk2(p1[8 * q + 2], p1[8 * q + 3]); w.z = pk2(p1[8 * q + 4], p1[8 * q + 5]); w.w = pk2(p1[8 * q + 6], p1[8 * q + 7]); }
;                         pf[s4] = __builtin_bit_cast(bf16x8, w);
;                     }
; #pragma unroll
;                     for (int s4 = 0; s4 < 4; ++s4) {
;                         if (s4 + 1 < 4) {
; #pragma unroll
;                             for (int i = 0; i < 4; ++i) vf[(s4 + 1) & 1][i] = *(const LAS bf16x8*)(vb + i * 32 * 144 + (s4 + 1) * 32);
;                         }
;                         __builtin_amdgcn_sched_barrier(0);
;                         #pragma unroll
;                         for (int i = 0; i < 4; ++i) o[i] = __builtin_amdgcn_mfma_f32_32x32x16_bf16(vf[s4 & 1][i], pf[s4], o[i], 0, 0, 0);
;                                                 __builtin_amdgcn_sched_barrier(0);
.Lat_noresc_b:
	v_exp_f32_e32 v96, v96
	v_exp_f32_e32 v97, v97
	v_exp_f32_e32 v98, v98
	v_exp_f32_e32 v99, v99
	v_exp_f32_e32 v100, v100
	v_exp_f32_e32 v101, v101
	v_exp_f32_e32 v102, v102
	v_exp_f32_e32 v103, v103
	v_add_f32_e32 v214, v96, v97
	v_add_f32_e32 v215, v98, v99
	v_add_f32_e32 v214, v214, v100
	v_add_f32_e32 v215, v215, v101
	v_add_f32_e32 v214, v214, v102
	v_add_f32_e32 v215, v215, v103
	v_cvt_pk_bf16_f32 v218, v96, v97
	v_cvt_pk_bf16_f32 v219, v98, v99
	v_cvt_pk_bf16_f32 v220, v100, v101
	v_cvt_pk_bf16_f32 v221, v102, v103
	v_add_f32_e32 v197, v197, v214
	v_add_f32_e32 v197, v197, v215
	s_waitcnt lgkmcnt(7)
	v_mfma_f32_32x32x16_bf16 v[64:79], v[152:155], v[218:221], v[64:79]
	v_exp_f32_e32 v104, v104
	v_exp_f32_e32 v105, v105
	v_exp_f32_e32 v106, v106
	v_exp_f32_e32 v107, v107
	v_exp_f32_e32 v108, v108
	s_waitcnt lgkmcnt(6)
	v_mfma_f32_32x32x16_bf16 v[48:63], v[10:13], v[218:221], v[48:63]
	v_exp_f32_e32 v109, v109
	v_exp_f32_e32 v110, v110
	v_exp_f32_e32 v111, v111
	v_add_f32_e32 v214, v104, v105
	v_add_f32_e32 v215, v106, v107
	s_waitcnt lgkmcnt(5)
	v_mfma_f32_32x32x16_bf16 v[32:47], v[6:9], v[218:221], v[32:47]
	v_add_f32_e32 v214, v214, v108
	v_add_f32_e32 v215, v215, v109
	v_add_f32_e32 v214, v214, v110
	v_add_f32_e32 v215, v215, v111
	v_cvt_pk_bf16_f32 v222, v104, v105
	s_waitcnt lgkmcnt(4)
	v_mfma_f32_32x32x16_bf16 v[16:31], v[2:5], v[218:221], v[16:31]
	v_cvt_pk_bf16_f32 v223, v106, v107
	v_cvt_pk_bf16_f32 v224, v108, v109
	v_cvt_pk_bf16_f32 v225, v110, v111
	v_add_f32_e32 v197, v197, v214
	v_add_f32_e32 v197, v197, v215
	ds_read_b128 v[152:155], v0 offset:36928
	ds_read_b128 v[10:13], v0 offset:41536
	ds_read_b128 v[6:9], v0 offset:46144
	ds_read_b128 v[2:5], v0 offset:50752
	s_waitcnt lgkmcnt(7)
	v_mfma_f32_32x32x16_bf16 v[64:79], v[198:201], v[222:225], v[64:79]
	v_exp_f32_e32 v80, v80
	v_exp_f32_e32 v81, v81
	v_exp_f32_e32 v82, v82
	v_exp_f32_e32 v83, v83
	v_exp_f32_e32 v84, v84
	s_waitcnt lgkmcnt(6)
	v_mfma_f32_32x32x16_bf16 v[48:63], v[202:205], v[222:225], v[48:63]
	v_exp_f32_e32 v85, v85
	v_exp_f32_e32 v86, v86
	v_exp_f32_e32 v87, v87
	v_add_f32_e32 v214, v80, v81
	v_add_f32_e32 v215, v82, v83
	s_waitcnt lgkmcnt(5)
	v_mfma_f32_32x32x16_bf16 v[32:47], v[206:209], v[222:225], v[32:47]
	v_add_f32_e32 v214, v214, v84
	v_add_f32_e32 v215, v215, v85
	v_add_f32_e32 v214, v214, v86
	v_add_f32_e32 v215, v215, v87
	v_cvt_pk_bf16_f32 v218, v80, v81
	s_waitcnt lgkmcnt(4)
	v_mfma_f32_32x32x16_bf16 v[16:31], v[210:213], v[222:225], v[16:31]
	v_cvt_pk_bf16_f32 v219, v82, v83
	v_cvt_pk_bf16_f32 v220, v84, v85
	v_cvt_pk_bf16_f32 v221, v86, v87
	v_add_f32_e32 v197, v197, v214
	v_add_f32_e32 v197, v197, v215
	ds_read_b128 v[198:201], v0 offset:36960
	ds_read_b128 v[202:205], v0 offset:41568
	ds_read_b128 v[206:209], v0 offset:46176
	ds_read_b128 v[210:213], v0 offset:50784
	s_waitcnt lgkmcnt(7)
	v_mfma_f32_32x32x16_bf16 v[64:79], v[152:155], v[218:221], v[64:79]
	v_exp_f32_e32 v88, v88
	v_exp_f32_e32 v89, v89
	v_exp_f32_e32 v90, v90
	v_exp_f32_e32 v91, v91
	v_exp_f32_e32 v92, v92
	s_waitcnt lgkmcnt(6)
	v_mfma_f32_32x32x16_bf16 v[48:63], v[10:13], v[218:221], v[48:63]
	v_exp_f32_e32 v93, v93
	v_exp_f32_e32 v94, v94
	v_exp_f32_e32 v95, v95
	v_add_f32_e32 v214, v88, v89
	v_add_f32_e32 v215, v90, v91
	s_waitcnt lgkmcnt(5)
	v_mfma_f32_32x32x16_bf16 v[32:47], v[6:9], v[218:221], v[32:47]
	v_add_f32_e32 v214, v214, v92
	v_add_f32_e32 v215, v215, v93
	v_add_f32_e32 v214, v214, v94
	v_add_f32_e32 v215, v215, v95
	v_cvt_pk_bf16_f32 v222, v88, v89
	s_waitcnt lgkmcnt(4)
	v_mfma_f32_32x32x16_bf16 v[16:31], v[2:5], v[218:221], v[16:31]
	v_cvt_pk_bf16_f32 v223, v90, v91
	v_cvt_pk_bf16_f32 v224, v92, v93
	v_cvt_pk_bf16_f32 v225, v94, v95
	v_add_f32_e32 v197, v197, v214
	v_add_f32_e32 v197, v197, v215
	s_waitcnt lgkmcnt(3)
	v_mfma_f32_32x32x16_bf16 v[64:79], v[198:201], v[222:225], v[64:79]
	s_waitcnt lgkmcnt(2)
	v_mfma_f32_32x32x16_bf16 v[48:63], v[202:205], v[222:225], v[48:63]
	s_waitcnt lgkmcnt(1)
	v_mfma_f32_32x32x16_bf16 v[32:47], v[206:209], v[222:225], v[32:47]
	s_waitcnt lgkmcnt(0)
	v_mfma_f32_32x32x16_bf16 v[16:31], v[210:213], v[222:225], v[16:31]
	s_branch .LBB0_124
	s_nop 0

; #define PG8_STAGE(bufoff, gbase, voff) do { _Pragma("unroll") for (int _i = 0; _i < 2; ++_i) \
;         __builtin_amdgcn_global_load_lds((const unsigned*)((const char*)(gbase) + (voff)[_i]), (PG8_LAS unsigned*)(lds + (bufoff) + ldsw + _i * 8192), 16, 0, 0); } while (0)
; #define PG8_LDA(dst, b, h) do { _Pragma("unroll") for (int m = 0; m < 4; ++m) _Pragma("unroll") for (int k = 0; k < 2; ++k) dst[m][k] = *(const PG8_LAS bf16x8*)(lds + PG8_SA(b, h) + aoff + m * 2048 + k * 1024); } while (0)
; #define PG8_LDB(dst, b, h) do { _Pragma("unroll") for (int n = 0; n < 2; ++n) _Pragma("unroll") for (int k = 0; k < 2; ++k) dst[n][k] = *(const PG8_LAS bf16x8*)(lds + PG8_SB(b, h) + boff + n * 2048 + k * 1024); } while (0)
; #define PG8_MMA(ai, bj, At, Bt) do { __builtin_amdgcn_s_setprio(1); _Pragma("unroll") for (int m = 0; m < 4; ++m) _Pragma("unroll") for (int n = 0; n < 2; ++n) _Pragma("unroll") for (int k = 0; k < 2; ++k) \
;         acc[ai][bj][m][n] = __builtin_amdgcn_mfma_f32_16x16x32_bf16(Bt[n][k], At[m][k], acc[ai][bj][m][n], 0, 0, 0); __builtin_amdgcn_s_setprio(0); } while (0)
; #define PG8_WAIT_V(n) asm volatile("s_waitcnt vmcnt(" #n ")" ::: "memory")
; #define PG8_WAIT_L(n) asm volatile("s_waitcnt lgkmcnt(" #n ")" ::: "memory")
; #define PG8_BAR __builtin_amdgcn_s_barrier()
; #define PG8_SCHED __builtin_amdgcn_sched_barrier(0)
; template <class Epi, class Sched, bool ALIGN_EPI = false, bool SP2 = false>
; __device__ __forceinline__ void gemm_phase(PG8_LAS unsigned char* lds, const Gemm g, const Sched& S, const Epi& E) {
;     ...
;             PG8_LDB(B0, 0, 0); PG8_LDB(B1, 0, 1); PG8_SCHED; PG8_LDA(At, 0, 0); PG8_STAGE(PG8_SA(1, 1), a1 + hstep, voffA);
;             PG8_WAIT_V(8); PG8_WAIT_L(0); PG8_BAR; PG8_MMA(0, 0, At, B0); PG8_MMA(0, 1, At, B1); PG8_BAR; PG8_SCHED;
;             PG8_LDA(At, 0, 1); PG8_STAGE(PG8_SB(0, 0), b2, voffB); PG8_STAGE(PG8_SB(0, 1), b2 + hstep, voffB); PG8_STAGE(PG8_SA(0, 0), a2, voffA);
;             PG8_WAIT_V(8); PG8_WAIT_L(0); PG8_BAR; PG8_MMA(1, 0, At, B0); PG8_MMA(1, 1, At, B1); PG8_BAR; PG8_SCHED;
.Lz_enter_568:
	s_add_u32 s10, s62, 0x80
	s_addc_u32 s11, s63, 0
	s_add_u32 s62, s20, 0x100
	s_addc_u32 s63, s21, 0
	s_mov_b32 s20, 0
	s_add_i32 m0, s64, 0xc000
	ds_read_b128 v[82:85], v246
	global_load_lds_dwordx4 v224, s[10:11]
	s_add_i32 m0, s64, 0xe000
	ds_read_b128 v[98:101], v246 offset:1024
	global_load_lds_dwordx4 v226, s[10:11]
	ds_read_b128 v[102:105], v246 offset:2048
	ds_read_b128 v[106:109], v246 offset:3072
	ds_read_b128 v[146:149], v246 offset:16384
	ds_read_b128 v[150:153], v246 offset:17408
	ds_read_b128 v[154:157], v246 offset:18432
	ds_read_b128 v[158:161], v246 offset:19456
	ds_read_b128 v[162:165], v249
	ds_read_b128 v[166:169], v249 offset:1024
	ds_read_b128 v[170:173], v249 offset:2048
	ds_read_b128 v[174:177], v249 offset:3072
	ds_read_b128 v[178:181], v249 offset:4096
	ds_read_b128 v[182:185], v249 offset:5120
	ds_read_b128 v[186:189], v249 offset:6144
	ds_read_b128 v[190:193], v249 offset:7168
	s_waitcnt vmcnt(8) lgkmcnt(0)
	s_barrier
	s_setprio 1
	v_mfma_f32_16x16x32_bf16 v[142:145], v[82:85], v[162:165], 0
	v_mfma_f32_16x16x32_bf16 v[138:141], v[102:105], v[162:165], 0
	v_mfma_f32_16x16x32_bf16 v[126:129], v[82:85], v[170:173], 0
	v_mfma_f32_16x16x32_bf16 v[122:125], v[102:105], v[170:173], 0
	s_add_i32 s78, s20, 2
	v_mfma_f32_16x16x32_bf16 v[110:113], v[82:85], v[178:181], 0
	s_add_u32 s79, s10, 0x80
	v_mfma_f32_16x16x32_bf16 v[94:97], v[102:105], v[178:181], 0
	s_addc_u32 s21, s11, 0
	v_mfma_f32_16x16x32_bf16 v[78:81], v[82:85], v[186:189], 0
	s_cmp_eq_u32 s68, s20
	v_mfma_f32_16x16x32_bf16 v[74:77], v[102:105], v[186:189], 0
	s_cselect_b32 s21, s59, s21
	v_mfma_f32_16x16x32_bf16 v[142:145], v[98:101], v[166:169], v[142:145]
	s_cselect_b32 s20, s58, s79
	v_mfma_f32_16x16x32_bf16 v[138:141], v[106:109], v[166:169], v[138:141]
	s_cselect_b32 s81, s61, s63
	v_mfma_f32_16x16x32_bf16 v[126:129], v[98:101], v[174:177], v[126:129]
	s_cselect_b32 s80, s60, s62
	v_mfma_f32_16x16x32_bf16 v[122:125], v[106:109], v[174:177], v[122:125]
	v_mfma_f32_16x16x32_bf16 v[110:113], v[98:101], v[182:185], v[110:113]
	v_mfma_f32_16x16x32_bf16 v[94:97], v[106:109], v[182:185], v[94:97]
	v_mfma_f32_16x16x32_bf16 v[78:81], v[98:101], v[190:193], v[78:81]
	v_mfma_f32_16x16x32_bf16 v[74:77], v[106:109], v[190:193], v[74:77]
	v_mfma_f32_16x16x32_bf16 v[134:137], v[146:149], v[162:165], 0
	v_mfma_f32_16x16x32_bf16 v[130:133], v[154:157], v[162:165], 0
	v_mfma_f32_16x16x32_bf16 v[118:121], v[146:149], v[170:173], 0
	v_mfma_f32_16x16x32_bf16 v[114:117], v[154:157], v[170:173], 0
	v_mfma_f32_16x16x32_bf16 v[90:93], v[146:149], v[178:181], 0
	v_mfma_f32_16x16x32_bf16 v[86:89], v[154:157], v[178:181], 0
	v_mfma_f32_16x16x32_bf16 v[70:73], v[146:149], v[186:189], 0
	v_mfma_f32_16x16x32_bf16 v[66:69], v[154:157], v[186:189], 0
	v_mfma_f32_16x16x32_bf16 v[134:137], v[150:153], v[166:169], v[134:137]
	v_mfma_f32_16x16x32_bf16 v[130:133], v[158:161], v[166:169], v[130:133]
	v_mfma_f32_16x16x32_bf16 v[118:121], v[150:153], v[174:177], v[118:121]
	v_mfma_f32_16x16x32_bf16 v[114:117], v[158:161], v[174:177], v[114:117]
	v_mfma_f32_16x16x32_bf16 v[90:93], v[150:153], v[182:185], v[90:93]
	v_mfma_f32_16x16x32_bf16 v[86:89], v[158:161], v[182:185], v[86:89]
	v_mfma_f32_16x16x32_bf16 v[70:73], v[150:153], v[190:193], v[70:73]
	v_mfma_f32_16x16x32_bf16 v[66:69], v[158:161], v[190:193], v[66:69]
	s_setprio 0
	s_barrier
	s_add_u32 s100, s80, s46
	s_addc_u32 s101, s81, s47
	s_add_i32 m0, s22, 0x10000
	ds_read_b128 v[162:165], v249 offset:16384
	global_load_lds_dwordx4 v0, s[80:81]
	s_add_i32 m0, s22, 0x12000
	ds_read_b128 v[166:169], v249 offset:17408
	global_load_lds_dwordx4 v218, s[80:81]
	s_add_i32 m0, s22, 0x14000
	ds_read_b128 v[170:173], v249 offset:18432
	global_load_lds_dwordx4 v0, s[100:101]
	s_add_i32 m0, s22, 0x16000
	ds_read_b128 v[174:177], v249 offset:19456
	global_load_lds_dwordx4 v218, s[100:101]
	s_mov_b32 m0, s64
	ds_read_b128 v[178:181], v249 offset:20480
	global_load_lds_dwordx4 v0, s[20:21]
	s_mov_b32 m0, s30
	ds_read_b128 v[182:185], v249 offset:21504
	global_load_lds_dwordx4 v218, s[20:21]
	ds_read_b128 v[186:189], v249 offset:22528
	ds_read_b128 v[190:193], v249 offset:23552
	s_waitcnt vmcnt(8) lgkmcnt(0)
	s_barrier
	s_setprio 1
	v_mfma_f32_16x16x32_bf16 v[62:65], v[82:85], v[162:165], 0
	v_mfma_f32_16x16x32_bf16 v[58:61], v[102:105], v[162:165], 0
	v_mfma_f32_16x16x32_bf16 v[46:49], v[82:85], v[170:173], 0
	v_mfma_f32_16x16x32_bf16 v[42:45], v[102:105], v[170:173], 0
	v_mfma_f32_16x16x32_bf16 v[30:33], v[82:85], v[178:181], 0
	v_mfma_f32_16x16x32_bf16 v[26:29], v[102:105], v[178:181], 0
	v_mfma_f32_16x16x32_bf16 v[14:17], v[82:85], v[186:189], 0
	v_mfma_f32_16x16x32_bf16 v[10:13], v[102:105], v[186:189], 0
	v_mfma_f32_16x16x32_bf16 v[62:65], v[98:101], v[166:169], v[62:65]
	v_mfma_f32_16x16x32_bf16 v[58:61], v[106:109], v[166:169], v[58:61]
	v_mfma_f32_16x16x32_bf16 v[46:49], v[98:101], v[174:177], v[46:49]
	v_mfma_f32_16x16x32_bf16 v[42:45], v[106:109], v[174:177], v[42:45]
	v_mfma_f32_16x16x32_bf16 v[30:33], v[98:101], v[182:185], v[30:33]
	v_mfma_f32_16x16x32_bf16 v[26:29], v[106:109], v[182:185], v[26:29]
	v_mfma_f32_16x16x32_bf16 v[14:17], v[98:101], v[190:193], v[14:17]
	v_mfma_f32_16x16x32_bf16 v[10:13], v[106:109], v[190:193], v[10:13]
	v_mfma_f32_16x16x32_bf16 v[54:57], v[146:149], v[162:165], 0
	v_mfma_f32_16x16x32_bf16 v[50:53], v[154:157], v[162:165], 0
	v_mfma_f32_16x16x32_bf16 v[38:41], v[146:149], v[170:173], 0
	v_mfma_f32_16x16x32_bf16 v[34:37], v[154:157], v[170:173], 0
	v_mfma_f32_16x16x32_bf16 v[22:25], v[146:149], v[178:181], 0
	v_mfma_f32_16x16x32_bf16 v[18:21], v[154:157], v[178:181], 0
	v_mfma_f32_16x16x32_bf16 v[6:9], v[146:149], v[186:189], 0
	v_mfma_f32_16x16x32_bf16 v[2:5], v[154:157], v[186:189], 0
	v_mfma_f32_16x16x32_bf16 v[54:57], v[150:153], v[166:169], v[54:57]
	v_mfma_f32_16x16x32_bf16 v[50:53], v[158:161], v[166:169], v[50:53]
	v_mfma_f32_16x16x32_bf16 v[38:41], v[150:153], v[174:177], v[38:41]
	v_mfma_f32_16x16x32_bf16 v[34:37], v[158:161], v[174:177], v[34:37]
	v_mfma_f32_16x16x32_bf16 v[22:25], v[150:153], v[182:185], v[22:25]
	v_mfma_f32_16x16x32_bf16 v[18:21], v[158:161], v[182:185], v[18:21]
	v_mfma_f32_16x16x32_bf16 v[6:9], v[150:153], v[190:193], v[6:9]
	v_mfma_f32_16x16x32_bf16 v[2:5], v[158:161], v[190:193], v[2:5]
	s_setprio 0
	s_barrier
; #define PG8_STAGE(bufoff, gbase, voff) do { _Pragma("unroll") for (int _i = 0; _i < 2; ++_i) \
;         __builtin_amdgcn_global_load_lds((const unsigned*)((const char*)(gbase) + (voff)[_i]), (PG8_LAS unsigned*)(lds + (bufoff) + ldsw + _i * 8192), 16, 0, 0); } while (0)
; #define PG8_LDA(dst, b, h) do { _Pragma("unroll") for (int m = 0; m < 4; ++m) _Pragma("unroll") for (int k = 0; k < 2; ++k) dst[m][k] = *(const PG8_LAS bf16x8*)(lds + PG8_SA(b, h) + aoff + m * 2048 + k * 1024); } while (0)
; #define PG8_LDB(dst, b, h) do { _Pragma("unroll") for (int n = 0; n < 2; ++n) _Pragma("unroll") for (int k = 0; k < 2; ++k) dst[n][k] = *(const PG8_LAS bf16x8*)(lds + PG8_SB(b, h) + boff + n * 2048 + k * 1024); } while (0)
; #define PG8_MMA(ai, bj, At, Bt) do { __builtin_amdgcn_s_setprio(1); _Pragma("unroll") for (int m = 0; m < 4; ++m) _Pragma("unroll") for (int n = 0; n < 2; ++n) _Pragma("unroll") for (int k = 0; k < 2; ++k) \
;         acc[ai][bj][m][n] = __builtin_amdgcn_mfma_f32_16x16x32_bf16(Bt[n][k], At[m][k], acc[ai][bj][m][n], 0, 0, 0); __builtin_amdgcn_s_setprio(0); } while (0)
; #define PG8_WAIT_V(n) asm volatile("s_waitcnt vmcnt(" #n ")" ::: "memory")
; #define PG8_WAIT_L(n) asm volatile("s_waitcnt lgkmcnt(" #n ")" ::: "memory")
; #define PG8_BAR __builtin_amdgcn_s_barrier()
; #define PG8_SCHED __builtin_amdgcn_sched_barrier(0)
; template <class Epi, class Sched, bool ALIGN_EPI = false, bool SP2 = false>
; __device__ __forceinline__ void gemm_phase(PG8_LAS unsigned char* lds, const Gemm g, const Sched& S, const Epi& E) {
;     ...
;             PG8_LDB(B0, 1, 0); PG8_LDB(B1, 1, 1); PG8_SCHED; PG8_LDA(At, 1, 0); PG8_STAGE(PG8_SA(0, 1), a2 + hstep, voffA);
;             PG8_WAIT_V(8); PG8_WAIT_L(0); PG8_BAR; PG8_MMA(0, 0, At, B0); PG8_MMA(0, 1, At, B1); PG8_BAR; PG8_SCHED;
;             PG8_LDA(At, 1, 1); PG8_STAGE(PG8_SB(1, 0), b3, voffB); PG8_STAGE(PG8_SB(1, 1), b3 + hstep, voffB); PG8_STAGE(PG8_SA(1, 0), a3, voffA);
;             PG8_WAIT_V(8); PG8_WAIT_L(0); PG8_BAR; PG8_MMA(1, 0, At, B0); PG8_MMA(1, 1, At, B1); PG8_BAR; PG8_SCHED;
	s_mov_b32 m0, s31
	ds_read_b128 v[82:85], v246 offset:32768
	global_load_lds_dwordx4 v224, s[20:21]
	s_mov_b32 m0, s33
	ds_read_b128 v[98:101], v246 offset:33792
	global_load_lds_dwordx4 v226, s[20:21]
	ds_read_b128 v[102:105], v246 offset:34816
	ds_read_b128 v[106:109], v246 offset:35840
	ds_read_b128 v[146:149], v246 offset:49152
	ds_read_b128 v[150:153], v246 offset:50176
	ds_read_b128 v[154:157], v246 offset:51200
	ds_read_b128 v[158:161], v246 offset:52224
	ds_read_b128 v[162:165], v249 offset:32768
	ds_read_b128 v[166:169], v249 offset:33792
	ds_read_b128 v[170:173], v249 offset:34816
	ds_read_b128 v[174:177], v249 offset:35840
	ds_read_b128 v[178:181], v249 offset:36864
	ds_read_b128 v[182:185], v249 offset:37888
	ds_read_b128 v[186:189], v249 offset:38912
	ds_read_b128 v[190:193], v249 offset:39936
	s_waitcnt vmcnt(8) lgkmcnt(0)
	s_barrier
	s_setprio 1
	v_mfma_f32_16x16x32_bf16 v[142:145], v[82:85], v[162:165], v[142:145]
	v_mfma_f32_16x16x32_bf16 v[138:141], v[102:105], v[162:165], v[138:141]
	v_mfma_f32_16x16x32_bf16 v[126:129], v[82:85], v[170:173], v[126:129]
	v_mfma_f32_16x16x32_bf16 v[122:125], v[102:105], v[170:173], v[122:125]
	v_mfma_f32_16x16x32_bf16 v[110:113], v[82:85], v[178:181], v[110:113]
	v_mfma_f32_16x16x32_bf16 v[94:97], v[102:105], v[178:181], v[94:97]
	v_mfma_f32_16x16x32_bf16 v[78:81], v[82:85], v[186:189], v[78:81]
	v_mfma_f32_16x16x32_bf16 v[74:77], v[102:105], v[186:189], v[74:77]
	v_mfma_f32_16x16x32_bf16 v[142:145], v[98:101], v[166:169], v[142:145]
	v_mfma_f32_16x16x32_bf16 v[138:141], v[106:109], v[166:169], v[138:141]
	v_mfma_f32_16x16x32_bf16 v[126:129], v[98:101], v[174:177], v[126:129]
	v_mfma_f32_16x16x32_bf16 v[122:125], v[106:109], v[174:177], v[122:125]
	v_mfma_f32_16x16x32_bf16 v[110:113], v[98:101], v[182:185], v[110:113]
	v_mfma_f32_16x16x32_bf16 v[94:97], v[106:109], v[182:185], v[94:97]
	v_mfma_f32_16x16x32_bf16 v[78:81], v[98:101], v[190:193], v[78:81]
	v_mfma_f32_16x16x32_bf16 v[74:77], v[106:109], v[190:193], v[74:77]
	v_mfma_f32_16x16x32_bf16 v[134:137], v[146:149], v[162:165], v[134:137]
	v_mfma_f32_16x16x32_bf16 v[130:133], v[154:157], v[162:165], v[130:133]
	v_mfma_f32_16x16x32_bf16 v[118:121], v[146:149], v[170:173], v[118:121]
	v_mfma_f32_16x16x32_bf16 v[114:117], v[154:157], v[170:173], v[114:117]
	v_mfma_f32_16x16x32_bf16 v[90:93], v[146:149], v[178:181], v[90:93]
	v_mfma_f32_16x16x32_bf16 v[86:89], v[154:157], v[178:181], v[86:89]
	v_mfma_f32_16x16x32_bf16 v[70:73], v[146:149], v[186:189], v[70:73]
	v_mfma_f32_16x16x32_bf16 v[66:69], v[154:157], v[186:189], v[66:69]
	v_mfma_f32_16x16x32_bf16 v[134:137], v[150:153], v[166:169], v[134:137]
	v_mfma_f32_16x16x32_bf16 v[130:133], v[158:161], v[166:169], v[130:133]
	v_mfma_f32_16x16x32_bf16 v[118:121], v[150:153], v[174:177], v[118:121]
	v_mfma_f32_16x16x32_bf16 v[114:117], v[158:161], v[174:177], v[114:117]
	v_mfma_f32_16x16x32_bf16 v[90:93], v[150:153], v[182:185], v[90:93]
	v_mfma_f32_16x16x32_bf16 v[86:89], v[158:161], v[182:185], v[86:89]
	v_mfma_f32_16x16x32_bf16 v[70:73], v[150:153], v[190:193], v[70:73]
	v_mfma_f32_16x16x32_bf16 v[66:69], v[158:161], v[190:193], v[66:69]
	s_setprio 0
	s_barrier
	s_add_i32 m0, s22, 0x17f80
	ds_read_b128 v[162:165], v249 offset:49152
	global_load_lds_dwordx4 v0, s[80:81] offset:128
	s_add_i32 m0, s22, 0x19f80
	ds_read_b128 v[166:169], v249 offset:50176
	global_load_lds_dwordx4 v218, s[80:81] offset:128
	s_add_i32 m0, s22, 0x1bf80
	ds_read_b128 v[170:173], v249 offset:51200
	global_load_lds_dwordx4 v0, s[100:101] offset:128
	s_add_i32 m0, s22, 0x1df80
	ds_read_b128 v[174:177], v249 offset:52224
	global_load_lds_dwordx4 v218, s[100:101] offset:128
	s_sub_i32 m0, s39, 0x80
	ds_read_b128 v[178:181], v249 offset:53248
	global_load_lds_dwordx4 v0, s[20:21] offset:128
	s_sub_i32 m0, s65, 0x80
	ds_read_b128 v[182:185], v249 offset:54272
	global_load_lds_dwordx4 v218, s[20:21] offset:128
	ds_read_b128 v[186:189], v249 offset:55296
	ds_read_b128 v[190:193], v249 offset:56320
	s_waitcnt vmcnt(8) lgkmcnt(0)
	s_barrier
	s_setprio 1
	v_mfma_f32_16x16x32_bf16 v[62:65], v[82:85], v[162:165], v[62:65]
	v_mfma_f32_16x16x32_bf16 v[58:61], v[102:105], v[162:165], v[58:61]
	v_mfma_f32_16x16x32_bf16 v[46:49], v[82:85], v[170:173], v[46:49]
	v_mfma_f32_16x16x32_bf16 v[42:45], v[102:105], v[170:173], v[42:45]
	s_add_u32 s10, s10, 0x100
	v_mfma_f32_16x16x32_bf16 v[30:33], v[82:85], v[178:181], v[30:33]
	s_addc_u32 s11, s11, 0
	v_mfma_f32_16x16x32_bf16 v[26:29], v[102:105], v[178:181], v[26:29]
	s_add_u32 s62, s62, 0x100
	v_mfma_f32_16x16x32_bf16 v[14:17], v[82:85], v[186:189], v[14:17]
	s_addc_u32 s63, s63, 0
	v_mfma_f32_16x16x32_bf16 v[10:13], v[102:105], v[186:189], v[10:13]
	s_mov_b32 s20, s78
	v_mfma_f32_16x16x32_bf16 v[62:65], v[98:101], v[166:169], v[62:65]
	v_mfma_f32_16x16x32_bf16 v[58:61], v[106:109], v[166:169], v[58:61]
	v_mfma_f32_16x16x32_bf16 v[46:49], v[98:101], v[174:177], v[46:49]
	v_mfma_f32_16x16x32_bf16 v[42:45], v[106:109], v[174:177], v[42:45]
	v_mfma_f32_16x16x32_bf16 v[30:33], v[98:101], v[182:185], v[30:33]
	v_mfma_f32_16x16x32_bf16 v[26:29], v[106:109], v[182:185], v[26:29]
	v_mfma_f32_16x16x32_bf16 v[14:17], v[98:101], v[190:193], v[14:17]
	v_mfma_f32_16x16x32_bf16 v[10:13], v[106:109], v[190:193], v[10:13]
	v_mfma_f32_16x16x32_bf16 v[54:57], v[146:149], v[162:165], v[54:57]
	v_mfma_f32_16x16x32_bf16 v[50:53], v[154:157], v[162:165], v[50:53]
	v_mfma_f32_16x16x32_bf16 v[38:41], v[146:149], v[170:173], v[38:41]
	v_mfma_f32_16x16x32_bf16 v[34:37], v[154:157], v[170:173], v[34:37]
	v_mfma_f32_16x16x32_bf16 v[22:25], v[146:149], v[178:181], v[22:25]
	v_mfma_f32_16x16x32_bf16 v[18:21], v[154:157], v[178:181], v[18:21]
	v_mfma_f32_16x16x32_bf16 v[6:9], v[146:149], v[186:189], v[6:9]
	v_mfma_f32_16x16x32_bf16 v[2:5], v[154:157], v[186:189], v[2:5]
	v_mfma_f32_16x16x32_bf16 v[54:57], v[150:153], v[166:169], v[54:57]
	v_mfma_f32_16x16x32_bf16 v[50:53], v[158:161], v[166:169], v[50:53]
	v_mfma_f32_16x16x32_bf16 v[38:41], v[150:153], v[174:177], v[38:41]
	v_mfma_f32_16x16x32_bf16 v[34:37], v[158:161], v[174:177], v[34:37]
	v_mfma_f32_16x16x32_bf16 v[22:25], v[150:153], v[182:185], v[22:25]
	v_mfma_f32_16x16x32_bf16 v[18:21], v[158:161], v[182:185], v[18:21]
	v_mfma_f32_16x16x32_bf16 v[6:9], v[150:153], v[190:193], v[6:9]
	v_mfma_f32_16x16x32_bf16 v[2:5], v[158:161], v[190:193], v[2:5]
	s_setprio 0
	s_barrier
	s_cmp_ge_i32 s78, s67
	s_cbranch_scc1 .Lpz_exit_570
	s_nop 0
